# prompt-item wave stagger s_sleep 32 instead of 24 on the all-to-all release version
# speedup vs baseline: 1.0085x; 1.0085x over previous
; template <bool SAMPLE> ...
;     ...
;     for (int d0 = 0; d0 < 4; ++d0) { const f32x4 g0 = *(const f32x4*)(qg + d0 * 16 + hi * 8), g1 = *(const f32x4*)(qg + d0 * 16 + hi * 8 + 4);
;         q[d0][0] *= rstd * g0.x; q[d0][1] *= rstd * g0.y; q[d0][2] *= rstd * g0.z; q[d0][3] *= rstd * g0.w; q[d0][4] *= rstd * g1.x; q[d0][5] *= rstd * g1.y; q[d0][6] *= rstd * g1.z; q[d0][7] *= rstd * g1.w; }
; __device__ __forceinline__ void attn_prompt_item(const Args& a, int l, int item, LAS unsigned char* lds, int tid, int lane, int wave) {
;     ...
;     __syncthreads();
;     attn_tile32<false>(qw0, zw0, Y, tab, qg, sinks, Kl + 32 * qt0 * 144, Vl + 32 * qt0 * 64, 16384, wsf, ost, rowq0, headw, b * 128 + qt0 * 32, (b == 0) ? 4 - qt0 : 0, lane);
.LBB0_475:
	s_or_b64 exec, exec, s[0:1]
	v_cmp_lt_i32_e32 vcc, v220, v214
	v_and_b32_e32 v172, 32, v132
	s_waitcnt lgkmcnt(0)
	v_cndmask_b32_e32 v16, v213, v220, vcc
	s_barrier
	v_lshlrev_b32_e32 v127, 2, v16
	global_load_dwordx4 v[16:19], v172, s[62:63]
	global_load_dwordx4 v[20:23], v172, s[62:63] offset:16
	global_load_dwordx4 v[24:27], v172, s[62:63] offset:64
	global_load_dwordx4 v[28:31], v172, s[62:63] offset:80
	global_load_dwordx4 v[32:35], v172, s[62:63] offset:128
	global_load_dwordx4 v[36:39], v172, s[62:63] offset:144
	global_load_dwordx4 v[40:43], v172, s[62:63] offset:192
	global_load_dwordx4 v[44:47], v172, s[62:63] offset:208
	v_readfirstlane_b32 s0, v208
	s_nop 3
	s_cmpk_lt_u32 s0, 0x100
	s_cbranch_scc1 .Lstg_skip
	s_sleep 32
